# combined: P0 transposes LDS-read batching + P7 dead zero-inits removed + P1 meta-row load batching + P3 scan meta-state loads hoisted
# speedup vs baseline: 1.0034x; 1.0034x over previous
; __global__ void __launch_bounds__(NTHR, 2) fwd_megakernel(Params p) {
;     ...
;                 const int q = ch & 63, g = (ch >> 6) & 63, b = ch >> 12;
;                 const float2 l16 = PW1[(g * 64 + q) * 16 + 15];
;                 const float* sp = Sst + ((size_t)(g * GRP + b * 128 + 32 * seg)) * 128 + q; bf16_t* xp = XS + ((size_t)(g * GRP + b * 128 + 32 * seg)) * XSK + 256 + q;
;                 float sr[32], si[32];
; #pragma unroll
;                 for (int k = 0; k < 32; ++k) { sr[k] = sp[(size_t)k * 128]; si[k] = sp[(size_t)k * 128 + 64]; }
;                 float hr = 0.f, hi = 0.f;
; #pragma unroll
;                 for (int k = 0; k < 32; ++k) { const float nr = l16.x * hr - l16.y * hi + sr[k], ni = l16.x * hi + l16.y * hr + si[k]; hr = nr; hi = ni; }
;                 tb[(seg * 128 + cl) * 2] = hr; tb[(seg * 128 + cl) * 2 + 1] = hi;
;                 __syncthreads();
;                 float pr = l16.x, pi = l16.y;
; #pragma unroll
;                 for (int e = 0; e < 5; ++e) { const float nr = pr * pr - pi * pi, ni = 2.0f * pr * pi; pr = nr; pi = ni; }
;                 hr = Sst[((size_t)(g * GRP + 1024)) * 128 + q]; hi = Sst[((size_t)(g * GRP + 1024)) * 128 + 64 + q];
.LBB0_644:
	v_add_u32_e32 v4, s8, v147
	v_bfe_u32 v46, v4, 6, 6
	s_ashr_i32 s6, s8, 5
	v_mul_u32_u24_e32 v8, 0x500, v46
	s_and_b32 s6, s6, 0xffffff80
	v_add3_u32 v40, s6, v48, v8
	v_ashrrev_i32_e32 v41, 31, v40
	v_lshlrev_b64 v[8:9], 9, v[40:41]
	v_lshl_add_u64 v[8:9], v[0:1], 0, v[8:9]
	v_add_co_u32_e32 v10, vcc, s9, v8
	v_lshl_or_b32 v4, v46, 13, v49
	s_nop 0
	v_addc_co_u32_e32 v11, vcc, 0, v9, vcc
	v_add_co_u32_e32 v12, vcc, s10, v8
	global_load_dword v83, v[8:9], off
	global_load_dword v82, v[8:9], off offset:256
	global_load_dword v38, v[8:9], off offset:512
	global_load_dword v39, v[8:9], off offset:768
	global_load_dword v81, v[8:9], off offset:1024
	global_load_dword v80, v[8:9], off offset:1280
	global_load_dword v34, v[8:9], off offset:1536
	global_load_dword v35, v[8:9], off offset:1792
	global_load_dword v79, v[8:9], off offset:2048
	global_load_dword v78, v[8:9], off offset:2304
	global_load_dword v32, v[8:9], off offset:2560
	global_load_dword v33, v[8:9], off offset:2816
	global_load_dword v77, v[8:9], off offset:3072
	global_load_dword v76, v[8:9], off offset:3328
	global_load_dword v30, v[8:9], off offset:3584
	global_load_dword v31, v[8:9], off offset:3840
	v_addc_co_u32_e32 v13, vcc, 0, v9, vcc
	v_add_co_u32_e32 v36, vcc, s11, v8
	global_load_dword v75, v[12:13], off offset:-4096
	global_load_dword v74, v[10:11], off offset:256
	global_load_dword v28, v[10:11], off offset:512
	global_load_dword v29, v[10:11], off offset:768
	global_load_dword v73, v[10:11], off offset:1024
	global_load_dword v72, v[10:11], off offset:1280
	global_load_dword v26, v[10:11], off offset:1536
	global_load_dword v27, v[10:11], off offset:1792
	global_load_dword v71, v[10:11], off offset:2048
	global_load_dword v70, v[10:11], off offset:2304
	global_load_dword v24, v[10:11], off offset:2560
	global_load_dword v25, v[10:11], off offset:2816
	global_load_dword v69, v[10:11], off offset:3072
	global_load_dword v68, v[10:11], off offset:3328
	global_load_dword v22, v[10:11], off offset:3584
	global_load_dword v23, v[10:11], off offset:3840
	global_load_dword v67, v[12:13], off
	global_load_dword v66, v[12:13], off offset:256
	global_load_dword v20, v[12:13], off offset:512
	global_load_dword v21, v[12:13], off offset:768
	global_load_dword v65, v[12:13], off offset:1024
	global_load_dword v64, v[12:13], off offset:1280
	global_load_dword v18, v[12:13], off offset:1536
	global_load_dword v19, v[12:13], off offset:1792
	global_load_dword v63, v[12:13], off offset:2048
	global_load_dword v62, v[12:13], off offset:2304
	global_load_dword v16, v[12:13], off offset:2560
	global_load_dword v17, v[12:13], off offset:2816
	global_load_dword v61, v[12:13], off offset:3072
	global_load_dword v60, v[12:13], off offset:3328
	global_load_dword v14, v[12:13], off offset:3584
	global_load_dword v15, v[12:13], off offset:3840
	v_addc_co_u32_e32 v37, vcc, 0, v9, vcc
	global_load_dword v59, v[36:37], off
	global_load_dword v58, v[36:37], off offset:256
	global_load_dword v12, v[36:37], off offset:512
	global_load_dword v13, v[36:37], off offset:768
	global_load_dword v57, v[36:37], off offset:1024
	global_load_dword v56, v[36:37], off offset:1280
	global_load_dword v10, v[36:37], off offset:1536
	global_load_dword v11, v[36:37], off offset:1792
	global_load_dword v55, v[36:37], off offset:2048
	global_load_dword v54, v[36:37], off offset:2304
	global_load_dword v8, v[36:37], off offset:2560
	global_load_dword v9, v[36:37], off offset:2816
	global_load_dword v53, v[36:37], off offset:3072
	global_load_dword v52, v[36:37], off offset:3328
	global_load_dword v42, v[36:37], off offset:3584
	global_load_dword v43, v[36:37], off offset:3840
	s_nop 0
	global_load_dwordx2 v[36:37], v4, s[34:35] offset:120
	v_mov_b32_e32 v86, v5
	s_mov_b64 s[6:7], 0x80000
	v_mul_u32_u24_e32 v246, 0x28000, v46
	v_mov_b32_e32 v247, 0
	v_lshlrev_b32_e32 v246, 2, v246
	v_lshl_add_u64 v[246:247], s[64:65], 0, v[246:247]
	v_lshl_add_u64 v[246:247], v[246:247], 0, v[6:7]
	v_lshl_add_u64 v[248:249], v[246:247], 0, s[6:7]
	global_load_dword v244, v[248:249], off
	global_load_dword v245, v[248:249], off offset:256
	s_waitcnt vmcnt(0)
	v_pk_mul_f32 v[44:45], v[36:37], 0 op_sel_hi:[1,0]
	s_nop 0
	v_add_f32_e32 v41, v45, v44
	v_sub_f32_e32 v4, v44, v45
	v_add_f32_e32 v44, v41, v82
	v_add_f32_e32 v4, v4, v83
	v_pk_mul_f32 v[44:45], v[36:37], v[44:45] op_sel:[1,0] op_sel_hi:[0,0]
	v_pk_fma_f32 v[84:85], v[36:37], v[4:5], v[44:45] neg_lo:[0,0,1] neg_hi:[0,0,1]
	v_pk_fma_f32 v[44:45], v[36:37], v[4:5], v[44:45] op_sel_hi:[1,0,1]
	s_nop 0
	v_mov_b32_e32 v85, v45
	v_pk_add_f32 v[44:45], v[84:85], v[38:39]
	s_nop 0
	v_pk_mul_f32 v[84:85], v[36:37], v[44:45]
	v_pk_mul_f32 v[44:45], v[36:37], v[44:45] op_sel:[1,0] op_sel_hi:[0,1]
	v_add_f32_e32 v41, v44, v45
	v_sub_f32_e32 v4, v84, v85
	v_add_f32_e32 v44, v41, v80
	v_add_f32_e32 v4, v4, v81
	v_pk_mul_f32 v[44:45], v[36:37], v[44:45] op_sel:[1,0] op_sel_hi:[0,0]
	v_pk_fma_f32 v[84:85], v[36:37], v[4:5], v[44:45] neg_lo:[0,0,1] neg_hi:[0,0,1]
	v_pk_fma_f32 v[44:45], v[36:37], v[4:5], v[44:45] op_sel_hi:[1,0,1]
	s_nop 0
	v_mov_b32_e32 v85, v45
	v_pk_add_f32 v[44:45], v[84:85], v[34:35]
	s_nop 0
	v_pk_mul_f32 v[84:85], v[36:37], v[44:45]
	v_pk_mul_f32 v[44:45], v[36:37], v[44:45] op_sel:[1,0] op_sel_hi:[0,1]
	v_add_f32_e32 v41, v44, v45
	v_sub_f32_e32 v4, v84, v85
	v_add_f32_e32 v44, v41, v78
	v_add_f32_e32 v4, v4, v79
	v_pk_mul_f32 v[44:45], v[36:37], v[44:45] op_sel:[1,0] op_sel_hi:[0,0]
	v_pk_fma_f32 v[84:85], v[36:37], v[4:5], v[44:45] neg_lo:[0,0,1] neg_hi:[0,0,1]
	v_pk_fma_f32 v[44:45], v[36:37], v[4:5], v[44:45] op_sel_hi:[1,0,1]
	s_nop 0
	v_mov_b32_e32 v85, v45
; __global__ void __launch_bounds__(NTHR, 2) fwd_megakernel(Params p) {
;     ...
;                 float hr = 0.f, hi = 0.f;
; #pragma unroll
;                 for (int k = 0; k < 32; ++k) { const float nr = l16.x * hr - l16.y * hi + sr[k], ni = l16.x * hi + l16.y * hr + si[k]; hr = nr; hi = ni; }
	v_pk_add_f32 v[44:45], v[84:85], v[32:33]
	s_nop 0
	v_pk_mul_f32 v[84:85], v[36:37], v[44:45]
	v_pk_mul_f32 v[44:45], v[36:37], v[44:45] op_sel:[1,0] op_sel_hi:[0,1]
	v_add_f32_e32 v41, v44, v45
	v_sub_f32_e32 v4, v84, v85
	v_add_f32_e32 v44, v41, v76
	v_add_f32_e32 v4, v4, v77
	v_pk_mul_f32 v[44:45], v[36:37], v[44:45] op_sel:[1,0] op_sel_hi:[0,0]
	v_pk_fma_f32 v[84:85], v[36:37], v[4:5], v[44:45] neg_lo:[0,0,1] neg_hi:[0,0,1]
	v_pk_fma_f32 v[44:45], v[36:37], v[4:5], v[44:45] op_sel_hi:[1,0,1]
	s_nop 0
	v_mov_b32_e32 v85, v45
	v_pk_add_f32 v[44:45], v[84:85], v[30:31]
	s_nop 0
	v_pk_mul_f32 v[84:85], v[36:37], v[44:45]
	v_pk_mul_f32 v[44:45], v[36:37], v[44:45] op_sel:[1,0] op_sel_hi:[0,1]
	v_add_f32_e32 v41, v44, v45
	v_sub_f32_e32 v4, v84, v85
	v_add_f32_e32 v44, v41, v74
	v_add_f32_e32 v4, v4, v75
	v_pk_mul_f32 v[44:45], v[36:37], v[44:45] op_sel:[1,0] op_sel_hi:[0,0]
	v_pk_fma_f32 v[84:85], v[36:37], v[4:5], v[44:45] neg_lo:[0,0,1] neg_hi:[0,0,1]
	v_pk_fma_f32 v[44:45], v[36:37], v[4:5], v[44:45] op_sel_hi:[1,0,1]
	s_nop 0
	v_mov_b32_e32 v85, v45
	v_pk_add_f32 v[44:45], v[84:85], v[28:29]
	s_nop 0
	v_pk_mul_f32 v[84:85], v[36:37], v[44:45]
	v_pk_mul_f32 v[44:45], v[36:37], v[44:45] op_sel:[1,0] op_sel_hi:[0,1]
	v_add_f32_e32 v41, v44, v45
	v_sub_f32_e32 v4, v84, v85
	v_add_f32_e32 v44, v41, v72
	v_add_f32_e32 v4, v4, v73
	v_pk_mul_f32 v[44:45], v[36:37], v[44:45] op_sel:[1,0] op_sel_hi:[0,0]
	v_pk_fma_f32 v[84:85], v[36:37], v[4:5], v[44:45] neg_lo:[0,0,1] neg_hi:[0,0,1]
	v_pk_fma_f32 v[44:45], v[36:37], v[4:5], v[44:45] op_sel_hi:[1,0,1]
	s_nop 0
	v_mov_b32_e32 v85, v45
	v_pk_add_f32 v[44:45], v[84:85], v[26:27]
	s_nop 0
	v_pk_mul_f32 v[84:85], v[36:37], v[44:45]
	v_pk_mul_f32 v[44:45], v[36:37], v[44:45] op_sel:[1,0] op_sel_hi:[0,1]
	v_add_f32_e32 v41, v44, v45
	v_sub_f32_e32 v4, v84, v85
	v_add_f32_e32 v44, v41, v70
	v_add_f32_e32 v4, v4, v71
	v_pk_mul_f32 v[44:45], v[36:37], v[44:45] op_sel:[1,0] op_sel_hi:[0,0]
	v_pk_fma_f32 v[84:85], v[36:37], v[4:5], v[44:45] neg_lo:[0,0,1] neg_hi:[0,0,1]
	v_pk_fma_f32 v[44:45], v[36:37], v[4:5], v[44:45] op_sel_hi:[1,0,1]
	s_nop 0
	v_mov_b32_e32 v85, v45
	v_pk_add_f32 v[44:45], v[84:85], v[24:25]
	s_nop 0
	v_pk_mul_f32 v[84:85], v[36:37], v[44:45]
	v_pk_mul_f32 v[44:45], v[36:37], v[44:45] op_sel:[1,0] op_sel_hi:[0,1]
	v_add_f32_e32 v41, v44, v45
	v_sub_f32_e32 v4, v84, v85
	v_add_f32_e32 v44, v41, v68
	v_add_f32_e32 v4, v4, v69
	v_pk_mul_f32 v[44:45], v[36:37], v[44:45] op_sel:[1,0] op_sel_hi:[0,0]
	v_pk_fma_f32 v[84:85], v[36:37], v[4:5], v[44:45] neg_lo:[0,0,1] neg_hi:[0,0,1]
	v_pk_fma_f32 v[44:45], v[36:37], v[4:5], v[44:45] op_sel_hi:[1,0,1]
	s_nop 0
	v_mov_b32_e32 v85, v45
	v_pk_add_f32 v[44:45], v[84:85], v[22:23]
	s_nop 0
	v_pk_mul_f32 v[84:85], v[36:37], v[44:45]
	v_pk_mul_f32 v[44:45], v[36:37], v[44:45] op_sel:[1,0] op_sel_hi:[0,1]
	v_add_f32_e32 v41, v44, v45
	v_sub_f32_e32 v4, v84, v85
	v_add_f32_e32 v44, v41, v66
	v_add_f32_e32 v4, v4, v67
	v_pk_mul_f32 v[44:45], v[36:37], v[44:45] op_sel:[1,0] op_sel_hi:[0,0]
	v_pk_fma_f32 v[84:85], v[36:37], v[4:5], v[44:45] neg_lo:[0,0,1] neg_hi:[0,0,1]
	v_pk_fma_f32 v[44:45], v[36:37], v[4:5], v[44:45] op_sel_hi:[1,0,1]
	s_nop 0
	v_mov_b32_e32 v85, v45
	v_pk_add_f32 v[44:45], v[84:85], v[20:21]
	s_nop 0
	v_pk_mul_f32 v[84:85], v[36:37], v[44:45]
	v_pk_mul_f32 v[44:45], v[36:37], v[44:45] op_sel:[1,0] op_sel_hi:[0,1]
	v_add_f32_e32 v41, v44, v45
	v_sub_f32_e32 v4, v84, v85
	v_add_f32_e32 v44, v41, v64
	v_add_f32_e32 v4, v4, v65
	v_pk_mul_f32 v[44:45], v[36:37], v[44:45] op_sel:[1,0] op_sel_hi:[0,0]
	v_pk_fma_f32 v[84:85], v[36:37], v[4:5], v[44:45] neg_lo:[0,0,1] neg_hi:[0,0,1]
	v_pk_fma_f32 v[44:45], v[36:37], v[4:5], v[44:45] op_sel_hi:[1,0,1]
	s_nop 0
	v_mov_b32_e32 v85, v45
	v_pk_add_f32 v[44:45], v[84:85], v[18:19]
	s_nop 0
	v_pk_mul_f32 v[84:85], v[36:37], v[44:45]
	v_pk_mul_f32 v[44:45], v[36:37], v[44:45] op_sel:[1,0] op_sel_hi:[0,1]
	v_add_f32_e32 v41, v44, v45
	v_sub_f32_e32 v4, v84, v85
	v_add_f32_e32 v44, v41, v62
	v_add_f32_e32 v4, v4, v63
	v_pk_mul_f32 v[44:45], v[36:37], v[44:45] op_sel:[1,0] op_sel_hi:[0,0]
	v_pk_fma_f32 v[84:85], v[36:37], v[4:5], v[44:45] neg_lo:[0,0,1] neg_hi:[0,0,1]
	v_pk_fma_f32 v[44:45], v[36:37], v[4:5], v[44:45] op_sel_hi:[1,0,1]
	s_nop 0
	v_mov_b32_e32 v85, v45
	v_pk_add_f32 v[44:45], v[84:85], v[16:17]
	s_nop 0
	v_pk_mul_f32 v[84:85], v[36:37], v[44:45]
	v_pk_mul_f32 v[44:45], v[36:37], v[44:45] op_sel:[1,0] op_sel_hi:[0,1]
	v_add_f32_e32 v41, v44, v45
	v_sub_f32_e32 v4, v84, v85
; __global__ void __launch_bounds__(NTHR, 2) fwd_megakernel(Params p) {
;     ...
;                 for (int k = 0; k < 32; ++k) { const float nr = l16.x * hr - l16.y * hi + sr[k], ni = l16.x * hi + l16.y * hr + si[k]; hr = nr; hi = ni; }
;                 tb[(seg * 128 + cl) * 2] = hr; tb[(seg * 128 + cl) * 2 + 1] = hi;
;                 __syncthreads();
;                 float pr = l16.x, pi = l16.y;
; #pragma unroll
;                 for (int e = 0; e < 5; ++e) { const float nr = pr * pr - pi * pi, ni = 2.0f * pr * pi; pr = nr; pi = ni; }
;                 hr = Sst[((size_t)(g * GRP + 1024)) * 128 + q]; hi = Sst[((size_t)(g * GRP + 1024)) * 128 + 64 + q];
; #pragma unroll
;                 for (int s2 = 0; s2 < 3; ++s2) { if (s2 < seg) { const float t2x = tb[(s2 * 128 + cl) * 2], t2y = tb[(s2 * 128 + cl) * 2 + 1]; const float nr = pr * hr - pi * hi + t2x, ni = pr * hi + pi * hr + t2y; hr = nr; hi = ni; } }
	v_add_f32_e32 v44, v41, v60
	v_add_f32_e32 v4, v4, v61
	v_pk_mul_f32 v[44:45], v[36:37], v[44:45] op_sel:[1,0] op_sel_hi:[0,0]
	v_pk_fma_f32 v[84:85], v[36:37], v[4:5], v[44:45] neg_lo:[0,0,1] neg_hi:[0,0,1]
	v_pk_fma_f32 v[44:45], v[36:37], v[4:5], v[44:45] op_sel_hi:[1,0,1]
	s_nop 0
	v_mov_b32_e32 v85, v45
	v_pk_add_f32 v[44:45], v[84:85], v[14:15]
	s_nop 0
	v_pk_mul_f32 v[84:85], v[36:37], v[44:45]
	v_pk_mul_f32 v[44:45], v[36:37], v[44:45] op_sel:[1,0] op_sel_hi:[0,1]
	v_add_f32_e32 v41, v44, v45
	v_sub_f32_e32 v4, v84, v85
	v_add_f32_e32 v44, v41, v58
	v_add_f32_e32 v4, v4, v59
	v_pk_mul_f32 v[44:45], v[36:37], v[44:45] op_sel:[1,0] op_sel_hi:[0,0]
	v_pk_fma_f32 v[84:85], v[36:37], v[4:5], v[44:45] neg_lo:[0,0,1] neg_hi:[0,0,1]
	v_pk_fma_f32 v[44:45], v[36:37], v[4:5], v[44:45] op_sel_hi:[1,0,1]
	s_nop 0
	v_mov_b32_e32 v85, v45
	v_pk_add_f32 v[44:45], v[84:85], v[12:13]
	s_nop 0
	v_pk_mul_f32 v[84:85], v[36:37], v[44:45]
	v_pk_mul_f32 v[44:45], v[36:37], v[44:45] op_sel:[1,0] op_sel_hi:[0,1]
	v_add_f32_e32 v41, v44, v45
	v_sub_f32_e32 v4, v84, v85
	v_add_f32_e32 v44, v41, v56
	v_add_f32_e32 v4, v4, v57
	v_pk_mul_f32 v[44:45], v[36:37], v[44:45] op_sel:[1,0] op_sel_hi:[0,0]
	v_pk_fma_f32 v[84:85], v[36:37], v[4:5], v[44:45] neg_lo:[0,0,1] neg_hi:[0,0,1]
	v_pk_fma_f32 v[44:45], v[36:37], v[4:5], v[44:45] op_sel_hi:[1,0,1]
	s_nop 0
	v_mov_b32_e32 v85, v45
	v_pk_add_f32 v[44:45], v[84:85], v[10:11]
	s_nop 0
	v_pk_mul_f32 v[84:85], v[36:37], v[44:45]
	v_pk_mul_f32 v[44:45], v[36:37], v[44:45] op_sel:[1,0] op_sel_hi:[0,1]
	v_add_f32_e32 v41, v44, v45
	v_sub_f32_e32 v4, v84, v85
	v_add_f32_e32 v44, v41, v54
	v_add_f32_e32 v4, v4, v55
	v_pk_mul_f32 v[44:45], v[36:37], v[44:45] op_sel:[1,0] op_sel_hi:[0,0]
	v_pk_fma_f32 v[84:85], v[36:37], v[4:5], v[44:45] neg_lo:[0,0,1] neg_hi:[0,0,1]
	v_pk_fma_f32 v[44:45], v[36:37], v[4:5], v[44:45] op_sel_hi:[1,0,1]
	s_nop 0
	v_mov_b32_e32 v85, v45
	v_pk_add_f32 v[44:45], v[84:85], v[8:9]
	s_nop 0
	v_pk_mul_f32 v[84:85], v[36:37], v[44:45]
	v_pk_mul_f32 v[44:45], v[36:37], v[44:45] op_sel:[1,0] op_sel_hi:[0,1]
	v_add_f32_e32 v41, v44, v45
	v_sub_f32_e32 v4, v84, v85
	v_add_f32_e32 v44, v41, v52
	v_add_f32_e32 v4, v4, v53
	v_pk_mul_f32 v[44:45], v[36:37], v[44:45] op_sel:[1,0] op_sel_hi:[0,0]
	v_pk_fma_f32 v[84:85], v[36:37], v[4:5], v[44:45] neg_lo:[0,0,1] neg_hi:[0,0,1]
	v_pk_fma_f32 v[44:45], v[36:37], v[4:5], v[44:45] op_sel_hi:[1,0,1]
	v_mul_f32_e32 v4, v37, v37
	v_mov_b32_e32 v85, v45
	v_pk_add_f32 v[42:43], v[84:85], v[42:43]
	ds_write_b64 v50, v[42:43]
	v_pk_fma_f32 v[42:43], v[36:37], v[36:37], v[4:5] op_sel_hi:[1,1,0] neg_lo:[0,0,1] neg_hi:[0,0,1]
	v_add_f32_e32 v4, v36, v36
	v_mul_f32_e32 v45, v4, v37
	v_mov_b32_e32 v4, v42
	v_mul_f32_e32 v44, v45, v45
	v_pk_mul_f32 v[84:85], v[42:43], v[4:5] op_sel_hi:[0,1]
	v_pk_fma_f32 v[42:43], v[42:43], v[4:5], v[44:45] op_sel_hi:[0,1,1] neg_lo:[0,0,1] neg_hi:[0,0,1]
	v_pk_mul_f32 v[44:45], v[84:85], v[44:45]
	v_add_f32_e32 v41, v42, v42
	v_mov_b32_e32 v43, v45
	v_pk_mul_f32 v[84:85], v[42:43], v[42:43]
	v_mul_f32_e32 v42, v41, v45
	v_sub_f32_e32 v4, v84, v85
	v_mul_f32_e32 v41, v4, v4
	v_fma_f32 v45, -v42, v42, v41
	v_add_f32_e32 v44, v4, v4
	v_mov_b32_e32 v43, v45
	v_mul_u32_u24_e32 v4, 0x28000, v46
	v_pk_mul_f32 v[42:43], v[44:45], v[42:43]
	v_lshlrev_b32_e32 v130, 2, v4
	v_pk_mov_b32 v[84:85], v[44:45], v[42:43] op_sel:[1,0]
	v_mov_b32_e32 v87, v42
	v_lshl_add_u64 v[46:47], s[64:65], 0, v[130:131]
	v_pk_mul_f32 v[44:45], v[84:85], v[86:87]
	v_lshl_add_u64 v[46:47], v[46:47], 0, v[6:7]
	v_pk_mul_f32 v[44:45], v[42:43], v[44:45]
	v_pk_fma_f32 v[42:43], v[84:85], v[86:87], v[42:43] neg_lo:[1,0,0] neg_hi:[1,0,0]
	v_lshl_add_u64 v[84:85], v[46:47], 0, s[6:7]
	v_add_co_u32_e32 v46, vcc, 0x80000, v46
	s_waitcnt lgkmcnt(0)
	s_nop 0
	v_addc_co_u32_e32 v47, vcc, 0, v47, vcc
	s_barrier
	v_mov_b32_e32 v46, v244
	v_mov_b32_e32 v47, v245
	s_and_saveexec_b64 s[6:7], s[52:53]
	s_cbranch_execz .LBB0_647
	v_mov_b32_e32 v84, v44
	v_mov_b32_e32 v85, v43
	s_waitcnt vmcnt(0)
	v_pk_mul_f32 v[84:85], v[84:85], v[46:47] op_sel:[0,1]
	v_pk_mov_b32 v[86:87], v[42:43], v[44:45] op_sel:[1,0]
	s_nop 0
	v_pk_fma_f32 v[88:89], v[86:87], v[46:47], v[84:85] neg_lo:[0,0,1] neg_hi:[0,0,1]
	v_pk_fma_f32 v[46:47], v[86:87], v[46:47], v[84:85] op_sel_hi:[1,0,1]
	s_nop 0
	v_mov_b32_e32 v89, v47
	ds_read_b64 v[46:47], v51
	s_waitcnt lgkmcnt(0)
	v_pk_add_f32 v[46:47], v[88:89], v[46:47]
	s_or_b64 exec, exec, s[6:7]
	s_and_saveexec_b64 s[6:7], s[54:55]
	s_cbranch_execnz .LBB0_648
